# NA loop: column-window mask folded into the QK MFMA C operand (0 or -1e30 per element, built once per unit), removing 32 v_cndmask per tile; bit-identical scores
# speedup vs baseline: 1.0057x; 1.0016x over previous
; #define ATT_MAX3(dst) do { float tm_ = max3f(sB0[0], sB1[0], sB0[1]), tn_ = max3f(sB1[1], sB0[2], sB1[2]); \
;         _Pragma("unroll") for (int r = 3; r < 15; r += 2) { tm_ = max3f(tm_, sB0[r], sB1[r]); tn_ = max3f(tn_, sB0[r + 1], sB1[r + 1]); } \
;         tm_ = max3f(tm_, sB0[15], sB1[15]); dst = max3f(tm_, tn_, tn_); } while (0)
; template <int MODE, bool FROZEN = false>
; __device__ __forceinline__ bool attn_unit(LAS unsigned char* lds, const Params& p, int l, int ua, int ub) {
;     ...
;     float cb_pos = 0.f, cb_neg = 0.f;
;     if constexpr (MODE == 1) { cb_pos = lut[448]; cb_neg = lut[0]; }
;     ATT_QK(0);
;     if constexpr (FROZEN) m_run = cb_neg;
;     { float tm0 = 0.f; if constexpr (!FROZEN) ATT_MAX3(tm0); ATT_BIAS(0, tm0); ATT_UPD(tm0); }
;     __syncthreads();
;     for (int t = 0; t < NT; ++t) {
.LBB0_257:
	v_add_f32_e32 v0, 0, v0
	v_max_f32_e32 v32, 0xf149f2ca, v0
	v_sub_f32_e32 v0, 0xf149f2ca, v32
	v_exp_f32_e32 v0, v0
	s_andn2_b64 vcc, exec, s[4:5]
	v_mul_f32_e32 v0, 0, v0
	v_cndmask_b32_e64 v0, v0, 0, s[0:1]
	v_mov_b32_e32 v1, v0
	v_mov_b32_e32 v2, v0
	v_mov_b32_e32 v3, v0
	v_mov_b32_e32 v4, v0
	v_mov_b32_e32 v5, v0
	v_mov_b32_e32 v6, v0
	v_mov_b32_e32 v7, v0
	v_mov_b32_e32 v8, v0
	v_mov_b32_e32 v9, v0
	v_mov_b32_e32 v10, v0
	v_mov_b32_e32 v11, v0
	v_mov_b32_e32 v12, v0
	v_mov_b32_e32 v13, v0
	v_mov_b32_e32 v14, v0
	v_mov_b32_e32 v15, v0
	v_mov_b32_e32 v16, v0
	v_mov_b32_e32 v17, v0
	v_mov_b32_e32 v18, v0
	v_mov_b32_e32 v19, v0
	v_mov_b32_e32 v20, v0
	v_mov_b32_e32 v21, v0
	v_mov_b32_e32 v22, v0
	v_mov_b32_e32 v23, v0
	v_mov_b32_e32 v24, v0
	v_mov_b32_e32 v25, v0
	v_mov_b32_e32 v26, v0
	v_mov_b32_e32 v27, v0
	v_mov_b32_e32 v28, v0
	v_mov_b32_e32 v29, v0
	v_mov_b32_e32 v30, v0
	v_mov_b32_e32 v31, v0
	s_cbranch_vccnz .LBB0_336
	v_add3_u32 v150, 0, v33, v196
	v_mov_b32_e32 v33, 0xf149f2ca
	v_cndmask_b32_e64 v152, v32, v33, s[0:1]
	v_min_u32_e32 v32, 48, v69
	v_sub_u32_e32 v32, v130, v32
	v_add_u32_e32 v35, 1, v32
	v_cmp_gt_u32_e64 s[42:43], 16, v35
	v_and_b32_e32 v35, -16, v35
	v_lshlrev_b32_e32 v33, 2, v68
	v_cmp_eq_u32_e64 s[44:45], s89, v35
	v_add_u32_e32 v35, 2, v32
	v_add3_u32 v151, 0, v196, v33
	v_and_b32_e32 v33, -16, v32
	v_cmp_gt_u32_e64 s[46:47], 16, v35
	v_and_b32_e32 v35, -16, v35
	v_cmp_eq_u32_e64 s[40:41], s89, v33
	v_cmp_eq_u32_e64 s[48:49], s89, v35
	v_add_u32_e32 v35, 3, v32
	v_cmp_eq_u32_e64 s[72:73], s88, v33
	v_add_u32_e32 v33, 17, v32
	v_cmp_gt_u32_e64 s[50:51], 16, v35
	v_and_b32_e32 v35, -16, v35
	s_movk_i32 s4, 0xffe0
	v_cmp_gt_u32_e64 s[74:75], 16, v33
	v_and_b32_e32 v33, -16, v33
	v_cmp_eq_u32_e64 s[52:53], s89, v35
	v_add_u32_e32 v35, 8, v32
	v_cmp_eq_u32_e64 s[76:77], s4, v33
	v_add_u32_e32 v33, 18, v32
	v_cmp_gt_u32_e64 s[54:55], 16, v35
	v_and_b32_e32 v35, -16, v35
	v_cmp_gt_u32_e64 s[78:79], 16, v33
	v_and_b32_e32 v33, -16, v33
	v_cmp_eq_u32_e64 s[56:57], s89, v35
	v_add_u32_e32 v35, 9, v32
	v_cmp_eq_u32_e64 s[80:81], s4, v33
	v_add_u32_e32 v33, 19, v32
	v_cmp_gt_u32_e64 s[58:59], 16, v35
	v_and_b32_e32 v35, -16, v35
	v_cmp_gt_u32_e64 s[82:83], 16, v33
	v_and_b32_e32 v33, -16, v33
	v_cmp_eq_u32_e64 s[60:61], s89, v35
	v_add_u32_e32 v35, 10, v32
	v_cmp_eq_u32_e64 s[84:85], s4, v33
	v_add_u32_e32 v33, 24, v32
	v_cmp_gt_u32_e64 s[62:63], 16, v35
	v_and_b32_e32 v35, -16, v35
	v_cmp_gt_u32_e64 s[86:87], 16, v33
	v_and_b32_e32 v33, -16, v33
	v_cmp_eq_u32_e64 s[64:65], s89, v35
	v_cmp_eq_u32_e64 s[88:89], s4, v33
	v_add_u32_e32 v33, 25, v32
	s_movk_i32 s0, 0xffef
	v_cmp_gt_u32_e64 s[90:91], 16, v33
	v_and_b32_e32 v33, -16, v33
	v_cmp_gt_u32_e64 s[38:39], 16, v32
	v_add_u32_e32 v35, 11, v32
	v_cmp_lt_u32_e64 s[70:71], s0, v32
	v_cmp_eq_u32_e64 s[92:93], s4, v33
	v_add_u32_e32 v33, 26, v32
	v_add_u32_e32 v32, 27, v32
	v_cmp_gt_u32_e64 s[66:67], 16, v35
	v_and_b32_e32 v35, -16, v35
	v_cmp_gt_u32_e64 s[94:95], 16, v33
	v_and_b32_e32 v33, -16, v33
	v_cmp_gt_u32_e64 s[0:1], 16, v32
	v_and_b32_e32 v32, -16, v32
	s_sub_i32 s11, s12, s11
	v_cmp_eq_u32_e64 s[68:69], s4, v35
	v_cmp_eq_u32_e64 s[96:97], s4, v33
	v_cmp_eq_u32_e64 s[4:5], s4, v32
	s_sub_i32 s19, s11, s10
	v_mov_b64_e32 v[32:33], v[30:31]
	s_add_i32 s17, s18, 12
	s_add_i32 s18, s18, 11
	s_add_i32 s19, s19, -3
	s_mov_b32 s21, 0
	v_mov_b64_e32 v[30:31], v[28:29]
	v_mov_b64_e32 v[28:29], v[26:27]
	v_mov_b64_e32 v[26:27], v[24:25]
	v_mov_b64_e32 v[24:25], v[22:23]
	v_mov_b64_e32 v[22:23], v[20:21]
	v_mov_b64_e32 v[20:21], v[18:19]
	v_mov_b64_e32 v[18:19], v[16:17]
	v_mov_b64_e32 v[16:17], v[14:15]
	v_mov_b64_e32 v[14:15], v[12:13]
	v_mov_b64_e32 v[12:13], v[10:11]
	v_mov_b64_e32 v[10:11], v[8:9]
	v_mov_b64_e32 v[8:9], v[6:7]
	v_mov_b64_e32 v[6:7], v[4:5]
	v_mov_b64_e32 v[4:5], v[2:3]
	v_mov_b64_e32 v[2:3], v[0:1]
	v_mov_b32_e32 v174, 0xf149f2ca
	s_nop 0
	v_cndmask_b32_e64 v202, v174, 0, s[38:39]
	v_cndmask_b32_e64 v176, v174, 0, s[40:41]
	v_cndmask_b32_e64 v203, v174, 0, s[42:43]
	v_cndmask_b32_e64 v177, v174, 0, s[44:45]
	v_cndmask_b32_e64 v204, v174, 0, s[46:47]
	v_cndmask_b32_e64 v178, v174, 0, s[48:49]
	v_cndmask_b32_e64 v205, v174, 0, s[50:51]
	v_cndmask_b32_e64 v179, v174, 0, s[52:53]
	v_cndmask_b32_e64 v206, v174, 0, s[54:55]
	v_cndmask_b32_e64 v180, v174, 0, s[56:57]
	v_cndmask_b32_e64 v207, v174, 0, s[58:59]
	v_cndmask_b32_e64 v181, v174, 0, s[60:61]
	v_cndmask_b32_e64 v208, v174, 0, s[62:63]
	v_cndmask_b32_e64 v182, v174, 0, s[64:65]
	v_cndmask_b32_e64 v209, v174, 0, s[66:67]
	v_cndmask_b32_e64 v183, v174, 0, s[68:69]
	v_cndmask_b32_e64 v210, v174, 0, s[70:71]
	v_cndmask_b32_e64 v184, v174, 0, s[72:73]
	v_cndmask_b32_e64 v211, v174, 0, s[74:75]
	v_cndmask_b32_e64 v185, v174, 0, s[76:77]
	v_cndmask_b32_e64 v212, v174, 0, s[78:79]
	v_cndmask_b32_e64 v186, v174, 0, s[80:81]
	v_cndmask_b32_e64 v213, v174, 0, s[82:83]
	v_cndmask_b32_e64 v187, v174, 0, s[84:85]
	v_cndmask_b32_e64 v214, v174, 0, s[86:87]
	v_cndmask_b32_e64 v188, v174, 0, s[88:89]
	v_cndmask_b32_e64 v215, v174, 0, s[90:91]
	v_cndmask_b32_e64 v189, v174, 0, s[92:93]
	v_cndmask_b32_e64 v216, v174, 0, s[94:95]
	v_cndmask_b32_e64 v190, v174, 0, s[96:97]
	v_cndmask_b32_e64 v217, v174, 0, s[0:1]
	v_cndmask_b32_e64 v191, v174, 0, s[4:5]
	s_add_i32 s23, s21, 2
	s_cmp_ge_i32 s23, s17
	s_cbranch_scc1 .LBB0_260

; #define LAS __attribute__((address_space(3)))
; #define SBAR_() __builtin_amdgcn_sched_barrier(0)
; template <int MODE, bool FROZEN = false>
; __device__ __forceinline__ bool attn_unit(LAS unsigned char* lds, const Params& p, int l, int ua, int ub) {
;     ...
;         {
;             const size_t advk = (size_t)min(t + 3, NT - 1) * 64 * NPROJ, advv = (size_t)min(t + 2, NT - 1) * 64;
; #pragma unroll
;             for (int i = 0; i < NKC; ++i) kr[i] = *(const u32x4*)(kvbase + advk + ksrc[i]);
; #pragma unroll
;             for (int i = 0; i < NVC; ++i) vr[i] = *(const u32x4*)(vtbase + advv + vsrc[i]);
;         }
;         f32x16 sA0 = sB0, sA1 = sB1;
;         const float c2 = cbB - m_run;
;         const LAS unsigned char* Vb = lds + OFF_V + (t & 1) * VBUF + vlane_off;
;         const LAS unsigned char* Kb = lds + OFF_K + ((t + 1) & 1) * KBUF + klane_off;
;     ...
;         bf16x8 kf0[4], kf1[4], va[NB], vb[NB], pf0, pf1; float ps0, ps1, ps2, ps3;
;         VLOAD(0, va);
;         EXPCVT(0, pf0, ps0);
;         SBAR_();
;         VLOAD(1, vb); PVMMA(va, pf0); EXPCVT(1, pf1, ps1); _Pragma("unroll") for (int g_ = 0; g_ < NB; ++g_) { __builtin_amdgcn_sched_group_barrier(0x008, 1, 0); __builtin_amdgcn_sched_group_barrier(0x100, 1, 0); __builtin_amdgcn_sched_group_barrier(0x400, 8 / NB, 0); __builtin_amdgcn_sched_group_barrier(0x002, 12 / NB, 0); } SBAR_();
;         VLOAD(2, va);
; #pragma unroll
;         for (int d0 = 0; d0 < 4; ++d0) { kf0[d0] = *(const LAS bf16x8*)(Kb + d0 * 32); kf1[d0] = *(const LAS bf16x8*)(Kb + 32 * KPB + d0 * 32); }
;         PVMMA(vb, pf1); EXPCVT(2, pf0, ps2); _Pragma("unroll") for (int g_ = 0; g_ < NB; ++g_) { __builtin_amdgcn_sched_group_barrier(0x008, 1, 0); __builtin_amdgcn_sched_group_barrier(0x100, 1, 0); __builtin_amdgcn_sched_group_barrier(0x400, 8 / NB, 0); __builtin_amdgcn_sched_group_barrier(0x002, 12 / NB, 0); } SBAR_();
;         {
;             f32x16 z0, z1;
; #pragma unroll
;             for (int r = 0; r < 16; ++r) { z0[r] = 0.f; z1[r] = 0.f; }
; #pragma unroll
;             for (int d0 = 0; d0 < 4; ++d0) { z0 = __builtin_amdgcn_mfma_f32_32x32x16_bf16(kf0[d0], qf[d0], z0, 0, 0, 0); z1 = __builtin_amdgcn_mfma_f32_32x32x16_bf16(kf1[d0], qf[d0], z1, 0, 0, 0); }
;             sB0 = z0; sB1 = z1;
;         }
;         EXPCVT(3, pf1, ps3);
; #pragma unroll
.LBB0_264:
	s_add_i32 s12, s21, 3
	s_min_i32 vcc_lo, s12, s18
	s_min_i32 s12, s23, s18
	s_ashr_i32 s13, s12, 31
	s_lshl_b64 s[12:13], s[12:13], 7
	v_mad_i64_i32 v[68:69], vcc, vcc_lo, v243, v[126:127]
	v_lshl_add_u64 v[70:71], v[128:129], 0, s[12:13]
	global_load_dwordx4 v[120:123], v[68:69], off
	global_load_dwordx4 v[116:119], v[70:71], off
	s_add_i32 s100, s21, 1
	s_cmp_lt_i32 s100, s16
	s_cbranch_scc1 .LBB0_334
	s_cmp_gt_i32 s21, s8
	s_cbranch_scc1 .LBB0_334
	v_add_f32_e64 v35, -v152, v52
	v_exp_f32_e32 v84, v35
	v_add_f32_e64 v35, -v152, v53
	v_exp_f32_e32 v86, v35
	v_add_f32_e64 v35, -v152, v54
	v_exp_f32_e32 v138, v35
	v_add_f32_e64 v35, -v152, v55
	v_exp_f32_e32 v142, v35
	v_add_f32_e64 v35, -v152, v56
	v_exp_f32_e32 v134, v35
	v_add_f32_e64 v35, -v152, v57
	s_bitcmp1_b32 s21, 0
	v_exp_f32_e32 v140, v35
	v_add_f32_e64 v35, -v152, v58
	s_cselect_b32 s12, 0x2400, 0
	v_exp_f32_e32 v132, v35
	v_add_f32_e64 v35, -v152, v59
	v_add_u32_e32 v1, s12, v150
	v_exp_f32_e32 v136, v35
	ds_read_b128 v[68:71], v1 offset:18432
	ds_read_b128 v[72:75], v1 offset:23040
	v_cvt_pk_bf16_f32 v52, v84, v86
	v_cvt_pk_bf16_f32 v53, v138, v142
	v_cvt_pk_bf16_f32 v54, v134, v140
	v_cvt_pk_bf16_f32 v55, v132, v136
	s_waitcnt lgkmcnt(1)
	s_nop 0
	v_mfma_f32_32x32x16_bf16 v[2:17], v[68:71], v[52:55], v[2:17]
	ds_read_b128 v[56:59], v1 offset:18464
	v_add_f32_e64 v60, -v152, v60
	v_exp_f32_e32 v98, v60
	v_add_f32_e64 v61, -v152, v61
	v_exp_f32_e32 v96, v61
	v_add_f32_e64 v62, -v152, v62
	v_exp_f32_e32 v146, v62
	v_add_f32_e64 v35, -v152, v64
	v_exp_f32_e32 v90, v35
	v_add_f32_e64 v35, -v152, v65
	v_exp_f32_e32 v94, v35
	v_add_f32_e64 v35, -v152, v66
	v_exp_f32_e32 v88, v35
	v_add_f32_e64 v35, -v152, v67
	v_exp_f32_e32 v92, v35
	v_add_f32_e64 v35, -v152, v63
	v_exp_f32_e32 v144, v35
	v_cvt_pk_bf16_f32 v62, v90, v94
	v_cvt_pk_bf16_f32 v63, v88, v92
	v_cvt_pk_bf16_f32 v61, v146, v144
	s_waitcnt lgkmcnt(1)
	v_mfma_f32_32x32x16_bf16 v[18:33], v[72:75], v[52:55], v[18:33]
	ds_read_b128 v[52:55], v1 offset:23072
	v_cvt_pk_bf16_f32 v60, v98, v96
	v_add_u32_e32 v35, s22, v149
	s_waitcnt lgkmcnt(1)
	v_mfma_f32_32x32x16_bf16 v[2:17], v[56:59], v[60:63], v[2:17]
	ds_read_b128 v[72:75], v1 offset:18496
	v_add_f32_e64 v36, -v152, v36
	v_exp_f32_e32 v85, v36
	v_add_f32_e64 v36, -v152, v43
	v_exp_f32_e32 v137, v36
	v_add_f32_e64 v37, -v152, v37
	v_exp_f32_e32 v87, v37
	v_add_f32_e64 v37, -v152, v42
	v_exp_f32_e32 v133, v37
	v_add_f32_e64 v38, -v152, v38
	v_exp_f32_e32 v139, v38
	v_add_f32_e64 v38, -v152, v41
	v_exp_f32_e32 v141, v38
	v_add_f32_e64 v39, -v152, v39
	v_exp_f32_e32 v143, v39
	v_add_f32_e64 v39, -v152, v40
	v_exp_f32_e32 v135, v39
	v_cvt_pk_bf16_f32 v83, v133, v137
	ds_read_b128 v[36:39], v35 offset:4608
	ds_read_b128 v[56:59], v35 offset:4640
	v_cvt_pk_bf16_f32 v82, v135, v141
	s_waitcnt lgkmcnt(3)
	v_mfma_f32_32x32x16_bf16 v[18:33], v[52:55], v[60:63], v[18:33]
	ds_read_b128 v[52:55], v35
	ds_read_b128 v[60:63], v35 offset:4672
	ds_read_b128 v[64:67], v35 offset:4704
	ds_read_b128 v[68:71], v1 offset:23104
	ds_read_b128 v[154:157], v35 offset:32
	ds_read_b128 v[158:161], v35 offset:64
	ds_read_b128 v[162:165], v35 offset:96
	v_cvt_pk_bf16_f32 v80, v85, v87
	v_cvt_pk_bf16_f32 v81, v139, v143
	v_add_f32_e64 v35, -v152, v51
	v_exp_f32_e32 v93, v35
	v_add_f32_e64 v35, -v152, v44
	v_exp_f32_e32 v99, v35
	v_add_f32_e64 v35, -v152, v46
	v_exp_f32_e32 v147, v35
	v_add_f32_e64 v35, -v152, v50
	v_exp_f32_e32 v89, v35
	v_add_f32_e64 v40, -v152, v45
	v_add_f32_e64 v76, -v152, v47
	v_add_f32_e64 v78, -v152, v48
	v_exp_f32_e32 v97, v40
	v_add_f32_e64 v79, -v152, v49
	s_waitcnt lgkmcnt(8)
	v_mfma_f32_32x32x16_bf16 v[36:51], v[36:39], v[100:103], v[176:191]
	s_waitcnt lgkmcnt(7)
	v_mfma_f32_32x32x16_bf16 v[36:51], v[56:59], v[104:107], v[36:51]
	s_waitcnt lgkmcnt(5)
	v_mfma_f32_32x32x16_bf16 v[36:51], v[60:63], v[108:111], v[36:51]
	s_waitcnt lgkmcnt(4)
	v_mfma_f32_32x32x16_bf16 v[36:51], v[64:67], v[112:115], v[36:51]
	v_mfma_f32_32x32x16_bf16 v[52:67], v[52:55], v[100:103], v[202:217]
	s_waitcnt lgkmcnt(2)
	v_mfma_f32_32x32x16_bf16 v[52:67], v[154:157], v[104:107], v[52:67]
	s_waitcnt lgkmcnt(1)
	v_mfma_f32_32x32x16_bf16 v[52:67], v[158:161], v[108:111], v[52:67]
	v_exp_f32_e32 v145, v76
	v_cvt_pk_bf16_f32 v76, v99, v97
	v_cvt_pk_bf16_f32 v77, v147, v145
	v_exp_f32_e32 v91, v78
	v_exp_f32_e32 v95, v79
	s_waitcnt lgkmcnt(0)
	v_mfma_f32_32x32x16_bf16 v[52:67], v[162:165], v[112:115], v[52:67]
	v_cvt_pk_bf16_f32 v79, v89, v93
	v_cvt_pk_bf16_f32 v78, v91, v95
	ds_read_b128 v[154:157], v1 offset:18528
	ds_read_b128 v[158:161], v1 offset:23136
	v_mfma_f32_32x32x16_bf16 v[2:17], v[72:75], v[80:83], v[2:17]
	v_add_f32_e64 v72, v138, v142
	v_add_f32_e64 v73, v139, v143
	v_add_f32_e64 v74, v134, v140
	v_add_f32_e64 v75, v135, v141
	v_add_f32_e64 v132, v132, v136
	v_add_f32_e64 v133, v133, v137
	v_pk_add_f32 v[84:85], v[84:85], v[86:87]
	v_pk_add_f32 v[74:75], v[74:75], v[132:133]
	s_andn2_b64 vcc, exec, s[10:11]
	v_mfma_f32_32x32x16_bf16 v[18:33], v[68:71], v[80:83], v[18:33]
	v_add_f32_e64 v68, v84, v72
	v_add_f32_e64 v69, v85, v73
	v_add_f32_e64 v72, v90, v94
	v_add_f32_e64 v73, v91, v95
	v_add_f32_e64 v68, v68, v74
	v_add_f32_e64 v69, v69, v75
	v_pk_add_f32 v[74:75], v[88:89], v[92:93]
	v_pk_add_f32 v[70:71], v[146:147], v[144:145]
	v_pk_add_f32 v[72:73], v[72:73], v[74:75]
	v_pk_add_f32 v[74:75], v[98:99], v[96:97]
	s_waitcnt lgkmcnt(1)
	v_mfma_f32_32x32x16_bf16 v[2:17], v[154:157], v[76:79], v[2:17]
	v_add_f32_e64 v70, v74, v70
	v_add_f32_e64 v71, v75, v71
	v_add_f32_e64 v70, v70, v72
	v_add_f32_e64 v71, v71, v73
	v_add_f32_e64 v68, v68, v70
	v_add_f32_e64 v69, v69, v71
	v_add_f32_e32 v1, v68, v69
	s_waitcnt lgkmcnt(0)
	v_mfma_f32_32x32x16_bf16 v[18:33], v[158:161], v[76:79], v[18:33]
	v_add_f32_e32 v0, v0, v1
	s_cbranch_vccnz .LBB0_334
	s_cmp_lt_i32 s20, s16
	s_cselect_b64 s[10:11], -1, 0
	s_cmp_ge_i32 s21, s8
	s_cselect_b64 s[12:13], -1, 0
	s_or_b64 s[10:11], s[12:13], s[10:11]
	s_and_b64 vcc, exec, s[10:11]
	s_cbranch_vccnz .LBB0_331
	s_add_i32 s10, s19, s21
	s_max_i32 s10, s10, -7
	s_add_i32 s10, s10, 7
	s_min_u32 s10, s10, 14
	s_mulk_i32 s10, 0x1fc
	v_add_u32_e32 v1, s10, v151
	v_mov_b32_e32 v35, 0xf149f2ca
	ds_read_b32 v68, v1 offset:36864
	ds_read_b32 v69, v1 offset:36992
	ds_read_b32 v70, v1 offset:36868
	ds_read_b32 v71, v1 offset:36996
	ds_read_b32 v72, v1 offset:36872
	ds_read_b32 v73, v1 offset:37000
	ds_read_b32 v74, v1 offset:36876
	ds_read_b32 v75, v1 offset:37004
	ds_read_b32 v76, v1 offset:36896
	ds_read_b32 v77, v1 offset:37024
	ds_read_b32 v78, v1 offset:36900
	ds_read_b32 v79, v1 offset:37028
	ds_read_b32 v80, v1 offset:36904
	ds_read_b32 v81, v1 offset:37032
	ds_read_b32 v82, v1 offset:36908
	s_waitcnt lgkmcnt(14)
	v_add_f32_e32 v52, v52, v68
	ds_read_b32 v83, v1 offset:37036
	s_waitcnt lgkmcnt(14)
	v_add_f32_e32 v36, v36, v69
	ds_read_b32 v84, v1 offset:36928
	s_waitcnt lgkmcnt(14)
	v_add_f32_e32 v53, v53, v70
	ds_read_b32 v85, v1 offset:37056
	s_waitcnt lgkmcnt(14)
	v_add_f32_e32 v37, v37, v71
	ds_read_b32 v86, v1 offset:36932
	s_waitcnt lgkmcnt(14)
	v_add_f32_e32 v54, v54, v72
	ds_read_b32 v87, v1 offset:37060
	s_waitcnt lgkmcnt(14)
	v_add_f32_e32 v38, v38, v73
	ds_read_b32 v88, v1 offset:36936
	s_waitcnt lgkmcnt(14)
	v_add_f32_e32 v55, v55, v74
	ds_read_b32 v89, v1 offset:37064
	s_waitcnt lgkmcnt(14)
	v_add_f32_e32 v39, v39, v75
	ds_read_b32 v90, v1 offset:36940
	s_waitcnt lgkmcnt(14)
	v_add_f32_e32 v56, v56, v76
	ds_read_b32 v91, v1 offset:37068
	s_waitcnt lgkmcnt(14)
	v_add_f32_e32 v40, v40, v77
	ds_read_b32 v92, v1 offset:36960
	s_waitcnt lgkmcnt(14)
	v_add_f32_e32 v57, v57, v78
	ds_read_b32 v93, v1 offset:37088
	s_waitcnt lgkmcnt(14)
	v_add_f32_e32 v41, v41, v79
	ds_read_b32 v94, v1 offset:36964
	s_waitcnt lgkmcnt(14)
	v_add_f32_e32 v58, v58, v80
	ds_read_b32 v95, v1 offset:37092
	s_waitcnt lgkmcnt(14)
	v_add_f32_e32 v42, v42, v81
	ds_read_b32 v96, v1 offset:36968
	s_waitcnt lgkmcnt(14)
	v_add_f32_e32 v59, v59, v82
	ds_read_b32 v97, v1 offset:37096
	s_waitcnt lgkmcnt(14)
	v_add_f32_e32 v43, v43, v83
	ds_read_b32 v98, v1 offset:36972
	s_waitcnt lgkmcnt(14)
	v_add_f32_e32 v60, v60, v84
	ds_read_b32 v99, v1 offset:37100
	s_waitcnt lgkmcnt(14)
	v_add_f32_e32 v44, v44, v85
	s_waitcnt lgkmcnt(13)
	v_add_f32_e32 v61, v61, v86
	s_waitcnt lgkmcnt(12)
	v_add_f32_e32 v45, v45, v87
	s_waitcnt lgkmcnt(11)
	v_add_f32_e32 v62, v62, v88
	s_waitcnt lgkmcnt(10)
	v_add_f32_e32 v46, v46, v89
	s_waitcnt lgkmcnt(9)
	v_add_f32_e32 v63, v63, v90
	s_waitcnt lgkmcnt(8)
	v_add_f32_e32 v47, v47, v91
	s_waitcnt lgkmcnt(7)
	v_add_f32_e32 v64, v64, v92
	s_waitcnt lgkmcnt(6)
	v_add_f32_e32 v48, v48, v93
	s_waitcnt lgkmcnt(5)
	v_add_f32_e32 v65, v65, v94
	s_waitcnt lgkmcnt(4)
	v_add_f32_e32 v49, v49, v95
	s_waitcnt lgkmcnt(3)
	v_add_f32_e32 v66, v66, v96
	s_waitcnt lgkmcnt(2)
	v_add_f32_e32 v50, v50, v97
	s_waitcnt lgkmcnt(1)
	v_add_f32_e32 v67, v67, v98
	s_waitcnt lgkmcnt(0)
	v_add_f32_e32 v51, v51, v99
	s_branch .LBB0_332
